# longer s_sleep between polls in the carry and row-statistics spin loops (less polling pressure on the memory system)
# speedup vs baseline: 1.0564x; 1.0101x over previous
.LBB0_499:
	global_load_dword v4, v[16:17], off sc1
	s_or_b64 s[62:63], s[62:63], exec
	s_waitcnt vmcnt(0)
	v_cmp_gt_u32_e32 vcc, 4, v4
	s_and_saveexec_b64 s[64:65], vcc
	s_cbranch_execz .LBB0_498
	s_cmp_lg_u32 s21, 0
	s_sleep 24
	s_cbranch_scc0 .LBB0_509
	global_load_dword v4, v[16:17], off sc1
	s_mov_b64 s[68:69], -1
	s_waitcnt vmcnt(0)
	v_cmp_gt_u32_e32 vcc, 4, v4
	s_and_saveexec_b64 s[66:67], vcc
	s_cbranch_execz .LBB0_496
	s_sleep 24
	global_load_dword v4, v[16:17], off sc1
	s_mov_b64 s[70:71], -1
	s_waitcnt vmcnt(0)
	v_cmp_gt_u32_e32 vcc, 4, v4
	s_and_saveexec_b64 s[68:69], vcc
	s_cbranch_execz .LBB0_495
	s_sleep 24
	global_load_dword v4, v[16:17], off sc1
	s_mov_b64 s[72:73], -1
	s_waitcnt vmcnt(0)
	v_cmp_gt_u32_e32 vcc, 4, v4
	s_and_saveexec_b64 s[70:71], vcc
	s_cbranch_execz .LBB0_494
	s_sleep 24
	global_load_dword v4, v[16:17], off sc1
	s_mov_b64 s[74:75], -1
	s_waitcnt vmcnt(0)
	v_cmp_gt_u32_e32 vcc, 4, v4
	s_and_saveexec_b64 s[72:73], vcc
	s_cbranch_execz .LBB0_493
	s_sleep 24
	global_load_dword v4, v[16:17], off sc1
	s_mov_b64 s[76:77], -1
	s_waitcnt vmcnt(0)
	v_cmp_gt_u32_e32 vcc, 4, v4
	s_and_saveexec_b64 s[74:75], vcc
	s_cbranch_execz .LBB0_492
	s_sleep 24
	global_load_dword v4, v[16:17], off sc1
	s_mov_b64 s[78:79], -1
	s_waitcnt vmcnt(0)
	v_cmp_gt_u32_e32 vcc, 4, v4
	s_and_saveexec_b64 s[76:77], vcc
	s_cbranch_execz .LBB0_491
	s_sleep 24
	global_load_dword v4, v[16:17], off sc1
	s_waitcnt vmcnt(0)
	v_cmp_gt_u32_e32 vcc, 4, v4
	s_and_saveexec_b64 s[80:81], vcc
	s_cbranch_execz .LBB0_490
	s_add_i32 s21, s21, -8
	s_xor_b64 s[78:79], exec, -1
	s_sleep 24
	s_branch .LBB0_490

.LBB0_522:
	global_load_dword v2, v[204:205], off sc1
	s_or_b64 s[62:63], s[62:63], exec
	s_waitcnt vmcnt(0)
	v_cmp_gt_u32_e32 vcc, 4, v2
	s_and_saveexec_b64 s[64:65], vcc
	s_cbranch_execz .LBB0_521
	s_cmp_lg_u32 s20, 0
	s_sleep 24
	s_cbranch_scc0 .LBB0_532
	global_load_dword v2, v[204:205], off sc1
	s_mov_b64 s[68:69], -1
	s_waitcnt vmcnt(0)
	v_cmp_gt_u32_e32 vcc, 4, v2
	s_and_saveexec_b64 s[66:67], vcc
	s_cbranch_execz .LBB0_519
	s_sleep 24
	global_load_dword v2, v[204:205], off sc1
	s_mov_b64 s[70:71], -1
	s_waitcnt vmcnt(0)
	v_cmp_gt_u32_e32 vcc, 4, v2
	s_and_saveexec_b64 s[68:69], vcc
	s_cbranch_execz .LBB0_518
	s_sleep 24
	global_load_dword v2, v[204:205], off sc1
	s_mov_b64 s[72:73], -1
	s_waitcnt vmcnt(0)
	v_cmp_gt_u32_e32 vcc, 4, v2
	s_and_saveexec_b64 s[70:71], vcc
	s_cbranch_execz .LBB0_517
	s_sleep 24
	global_load_dword v2, v[204:205], off sc1
	s_mov_b64 s[74:75], -1
	s_waitcnt vmcnt(0)
	v_cmp_gt_u32_e32 vcc, 4, v2
	s_and_saveexec_b64 s[72:73], vcc
	s_cbranch_execz .LBB0_516
	s_sleep 24
	global_load_dword v2, v[204:205], off sc1
	s_mov_b64 s[76:77], -1
	s_waitcnt vmcnt(0)
	v_cmp_gt_u32_e32 vcc, 4, v2
	s_and_saveexec_b64 s[74:75], vcc
	s_cbranch_execz .LBB0_515
	s_sleep 24
	global_load_dword v2, v[204:205], off sc1
	s_mov_b64 s[78:79], -1
	s_waitcnt vmcnt(0)
	v_cmp_gt_u32_e32 vcc, 4, v2
	s_and_saveexec_b64 s[76:77], vcc
	s_cbranch_execz .LBB0_514
	s_sleep 24
	global_load_dword v2, v[204:205], off sc1
	s_waitcnt vmcnt(0)
	v_cmp_gt_u32_e32 vcc, 4, v2
	s_and_saveexec_b64 s[80:81], vcc
	s_cbranch_execz .LBB0_513
	s_add_i32 s20, s20, -8
	s_xor_b64 s[78:79], exec, -1
	s_sleep 24
	s_branch .LBB0_513

.LBB0_629:
	global_load_dword v40, v161, s[2:3] sc1
	s_mov_b64 s[66:67], -1
	s_waitcnt vmcnt(0)
	v_readfirstlane_b32 s16, v40
	s_cmp_gt_u32 s16, 15
	s_cbranch_scc1 .LBB0_628
	s_sleep 20
	global_load_dword v40, v161, s[2:3] sc1
	s_waitcnt vmcnt(0)
	v_readfirstlane_b32 s16, v40
	s_cmp_lt_u32 s16, 16
	s_cbranch_scc0 .LBB0_628
	s_sleep 20
	global_load_dword v40, v161, s[2:3] sc1
	s_waitcnt vmcnt(0)
	v_readfirstlane_b32 s16, v40
	s_cmp_lt_u32 s16, 16
	s_cbranch_scc0 .LBB0_628
	s_add_i32 s15, s15, -3
	s_cmp_eq_u32 s15, 0
	s_cselect_b64 s[66:67], -1, 0
	s_sleep 20
	s_branch .LBB0_628

.LBB0_822:
	global_load_dword v142, v161, s[8:9] sc1
	s_waitcnt vmcnt(0)
	v_readfirstlane_b32 s10, v142
	s_cmp_gt_u32 s10, 15
	s_mov_b64 s[10:11], -1
	s_cbranch_scc1 .LBB0_821
	s_sleep 20
	global_load_dword v142, v161, s[8:9] sc1
	s_waitcnt vmcnt(0)
	v_readfirstlane_b32 s10, v142
	s_cmp_lt_u32 s10, 16
	s_mov_b64 s[10:11], -1
	s_cbranch_scc0 .LBB0_821
	s_sleep 20
	global_load_dword v142, v161, s[8:9] sc1
	s_waitcnt vmcnt(0)
	v_readfirstlane_b32 s10, v142
	s_cmp_lt_u32 s10, 16
	s_mov_b64 s[10:11], -1
	s_cbranch_scc0 .LBB0_821
	s_add_i32 s12, s12, -3
	s_cmp_eq_u32 s12, 0
	s_cselect_b64 s[10:11], -1, 0
	s_sleep 20
	s_branch .LBB0_821
